# LRU tile loop VALU trim: sigmoid bias folded into one v_fma (bias pre-multiplied per unit), sqrt(max(1-a*a,0)) via fma clamp; 48 VALU per tile replaced by s_nop
# speedup vs baseline: 1.0044x; 1.0044x over previous
; #define GAS __attribute__((address_space(1)))
; #define LAS __attribute__((address_space(3)))
; __device__ __forceinline__ v4u pack8(const float* v) { v4u w; w.x = pk2(v[0], v[1]); w.y = pk2(v[2], v[3]); w.z = pk2(v[4], v[5]); w.w = pk2(v[6], v[7]); return w; }
; __device__ __forceinline__ void lru_unit(Frame& F, int seq, int n) {
;     ...
;     const int dl = 16 * w + (lane & 15), tq = lane >> 4, dg = 128 * n + dl;
;     const float brg = F.in[11][dg], big = F.in[13][dg];
;     float nsp; { const float x = -F.in[14][dg]; const float sp = fmaxf(x, 0.f) + log1pf(expf(-fabsf(x))); nsp = -8.f * LOG2E * sp; }
;     bf16x8 Br[4], Bi[4];
;     { const bf16* WG = (const bf16*)(F.ws + WS_WG) + (size_t)(2 * n) * 16384;
; #pragma unroll
;       for (int kk = 0; kk < 4; ++kk) { Br[kk] = *(const GAS bf16x8*)(WG + (size_t)dl * 128 + 32 * kk + 8 * tq); Bi[kk] = *(const GAS bf16x8*)(WG + 16384 + (size_t)dl * 128 + 32 * kk + 8 * tq); } }
;     float hc = smp ? F.in[5][b * DM + dg] : 0.f;
;     if (tid < 48) { const int hr = tid >> 4; float x[8];
;         if (smp) { const GAS f32x4* sp_ = (const GAS f32x4*)(F.in[4] + (size_t)(b * 3 + hr) * DM + c0); const f32x4 s0 = sp_[0], s1 = sp_[1];
;             x[0] = s0.x; x[1] = s0.y; x[2] = s0.z; x[3] = s0.w; x[4] = s1.x; x[5] = s1.y; x[6] = s1.z; x[7] = s1.w; }
;         else {
; #pragma unroll
;             for (int e = 0; e < 8; ++e) x[e] = 0.f; }
;         *(LAS v4u*)(HALO + hr * 136 + 8 * cg) = pack8(x); }
;     v4u xr0, xr1; unsigned short zc[16], zn[16];
;     const bf16* xsrc = XA + (rowbase + ct) * DM + c0; const bf16* zsrc = ZA + (rowbase + 4 * tq) * DM + dg;
;     xr0 = *(const GAS v4u*)(xsrc); xr1 = *(const GAS v4u*)(xsrc + (size_t)32 * DM);
; #pragma unroll
;     for (int i = 0; i < 16; ++i) zc[i] = *(const GAS unsigned short*)(zsrc + (size_t)(16 * (i >> 2) + (i & 3)) * DM);
.LBB0_437:
	s_or_b64 exec, exec, s[4:5]
	s_waitcnt vmcnt(8)
	s_mov_b32 s90, 0xbfb8aa3b
	v_mul_f32_e32 v143, 0xbfb8aa3b, v143
	v_mul_f32_e32 v144, 0xbfb8aa3b, v144
	v_mul_f32_e64 v74, |v85|, s15
	v_rndne_f32_e32 v75, v74
	v_sub_f32_e32 v76, v74, v75
	v_fma_f32 v74, |v85|, s15, -v74
	s_mov_b32 s0, 0xb2a5705f
	v_fma_f32 v74, |v85|, s0, v74
	v_add_f32_e32 v74, v76, v74
	v_exp_f32_e32 v74, v74
	v_cvt_i32_f32_e32 v75, v75
	s_mov_b32 s0, 0x42ce8ed0
	v_cmp_ngt_f32_e64 vcc, |v85|, s0
	v_max_f32_e64 v76, -v85, -v85
	v_ldexp_f32 v74, v74, v75
	v_cndmask_b32_e32 v74, 0, v74, vcc
	v_cmp_nlt_f32_e64 vcc, |v85|, s34
	v_max_f32_e32 v100, 0, v76
	s_movk_i32 s0, 0x1000
	v_cndmask_b32_e32 v101, v127, v74, vcc
	v_add_f32_e32 v76, 1.0, v101
	v_add_f32_e32 v74, -1.0, v76
	v_sub_f32_e32 v75, v74, v76
	v_add_f32_e32 v75, 1.0, v75
	v_sub_f32_e32 v74, v101, v74
	v_add_f32_e32 v77, v74, v75
	v_frexp_mant_f32_e32 v78, v76
	v_cvt_f64_f32_e32 v[74:75], v76
	v_frexp_exp_i32_f64_e32 v74, v[74:75]
	v_cmp_gt_f32_e32 vcc, s50, v78
	v_add_u32_e32 v151, 0x2200, v83
	v_cmp_eq_u32_e64 s[4:5], 0, v91
	v_subbrev_co_u32_e32 v74, vcc, 0, v74, vcc
	v_sub_u32_e32 v75, 0, v74
	v_ldexp_f32 v76, v76, v75
	v_ldexp_f32 v75, v77, v75
	v_add_f32_e32 v77, -1.0, v76
	v_add_f32_e32 v80, 1.0, v76
	v_add_f32_e32 v78, 1.0, v77
	v_add_f32_e32 v81, -1.0, v80
	v_sub_f32_e32 v78, v76, v78
	v_sub_f32_e32 v76, v76, v81
	v_add_f32_e32 v78, v75, v78
	v_add_f32_e32 v75, v75, v76
	v_add_f32_e32 v76, v80, v75
	v_rcp_f32_e32 v81, v76
	v_add_f32_e32 v79, v77, v78
	v_sub_f32_e32 v77, v77, v79
	v_add_f32_e32 v77, v78, v77
	v_sub_f32_e32 v78, v80, v76
	v_add_f32_e32 v75, v75, v78
	v_mul_f32_e32 v78, v79, v81
	v_mul_f32_e32 v80, v76, v78
	v_fma_f32 v85, v78, v76, -v80
	v_fmac_f32_e32 v85, v78, v75
	v_add_f32_e32 v86, v80, v85
	v_sub_f32_e32 v87, v79, v86
	v_sub_f32_e32 v79, v79, v87
	v_sub_f32_e32 v80, v86, v80
	v_sub_f32_e32 v79, v79, v86
	v_add_f32_e32 v77, v77, v79
	v_sub_f32_e32 v79, v80, v85
	v_add_f32_e32 v77, v79, v77
	v_add_f32_e32 v79, v87, v77
	v_mul_f32_e32 v80, v81, v79
	v_mul_f32_e32 v85, v76, v80
	v_fma_f32 v76, v80, v76, -v85
	v_fmac_f32_e32 v76, v80, v75
	v_sub_f32_e32 v75, v87, v79
	v_add_f32_e32 v75, v77, v75
	v_add_f32_e32 v77, v85, v76
	v_sub_f32_e32 v86, v79, v77
	v_sub_f32_e32 v79, v79, v86
	v_sub_f32_e32 v85, v77, v85
	v_sub_f32_e32 v77, v79, v77
	v_add_f32_e32 v75, v75, v77
	v_sub_f32_e32 v76, v85, v76
	v_cvt_f32_i32_e32 v74, v74
	v_add_f32_e32 v75, v76, v75
	v_add_f32_e32 v76, v78, v80
	v_add_f32_e32 v75, v86, v75
	v_sub_f32_e32 v77, v76, v78
	v_mul_f32_e32 v75, v81, v75
	v_sub_f32_e32 v77, v80, v77
	v_add_f32_e32 v75, v77, v75
	v_mul_f32_e32 v80, 0x3f317218, v74
	v_add_f32_e32 v77, v76, v75
	v_fma_f32 v81, v74, s51, -v80
	v_mul_f32_e32 v78, v77, v77
	v_fmac_f32_e32 v81, 0xb102e308, v74
	v_fmamk_f32 v79, v78, 0x3e9b6dac, v126
	v_sub_f32_e32 v74, v77, v76
	v_add_f32_e32 v102, v80, v81
	v_fmaak_f32 v79, v78, v79, 0x3f2aaada
	v_sub_f32_e32 v74, v75, v74
	v_sub_f32_e32 v75, v102, v80
	v_mul_f32_e32 v76, v77, v78
	v_sub_f32_e32 v103, v81, v75
	v_ldexp_f32 v75, v77, 1
	v_mul_f32_e32 v76, v76, v79
	v_add_f32_e32 v77, v75, v76
	v_sub_f32_e32 v75, v77, v75
	v_ldexp_f32 v74, v74, 1
	v_sub_f32_e32 v75, v76, v75
	v_add_f32_e32 v74, v74, v75
	v_add_f32_e32 v104, v77, v74
	v_sub_f32_e32 v75, v104, v77
	v_ashrrev_i32_e32 v85, 31, v84
	v_sub_f32_e32 v105, v74, v75
	v_lshl_add_u64 v[74:75], s[44:45], 0, v[84:85]
	v_lshlrev_b64 v[74:75], 11, v[74:75]
	v_lshl_add_u64 v[74:75], s[10:11], 0, v[74:75]
	v_lshlrev_b32_e32 v76, 1, v92
	v_mov_b32_e32 v77, v115
	v_lshl_add_u64 v[116:117], v[74:75], 0, v[76:77]
	v_lshlrev_b32_e32 v74, 2, v91
	v_mov_b32_e32 v75, v115
	v_lshl_add_u64 v[74:75], s[44:45], 0, v[74:75]
	v_lshlrev_b64 v[74:75], 11, v[74:75]
	v_lshl_add_u64 v[74:75], s[28:29], 0, v[74:75]
	v_lshlrev_b32_e32 v76, 1, v114
	v_add_co_u32_e32 v78, vcc, s57, v116
	v_lshl_add_u64 v[118:119], v[74:75], 0, v[76:77]
	s_nop 0
	v_addc_co_u32_e32 v79, vcc, 0, v117, vcc
	v_add_co_u32_e32 v86, vcc, s0, v118
	s_mov_b32 s0, 0x8000
	s_nop 0
; #define GAS __attribute__((address_space(1)))
; #define LAS __attribute__((address_space(3)))
; __device__ __forceinline__ v4u pack8(const float* v) { v4u w; w.x = pk2(v[0], v[1]); w.y = pk2(v[2], v[3]); w.z = pk2(v[4], v[5]); w.w = pk2(v[6], v[7]); return w; }
; __device__ __forceinline__ void lru_unit(Frame& F, int seq, int n) {
;     ...
;     float nsp; { const float x = -F.in[14][dg]; const float sp = fmaxf(x, 0.f) + log1pf(expf(-fabsf(x))); nsp = -8.f * LOG2E * sp; }
;     bf16x8 Br[4], Bi[4];
;     { const bf16* WG = (const bf16*)(F.ws + WS_WG) + (size_t)(2 * n) * 16384;
; #pragma unroll
;       for (int kk = 0; kk < 4; ++kk) { Br[kk] = *(const GAS bf16x8*)(WG + (size_t)dl * 128 + 32 * kk + 8 * tq); Bi[kk] = *(const GAS bf16x8*)(WG + 16384 + (size_t)dl * 128 + 32 * kk + 8 * tq); } }
;     float hc = smp ? F.in[5][b * DM + dg] : 0.f;
;     if (tid < 48) { const int hr = tid >> 4; float x[8];
;         if (smp) { const GAS f32x4* sp_ = (const GAS f32x4*)(F.in[4] + (size_t)(b * 3 + hr) * DM + c0); const f32x4 s0 = sp_[0], s1 = sp_[1];
;             x[0] = s0.x; x[1] = s0.y; x[2] = s0.z; x[3] = s0.w; x[4] = s1.x; x[5] = s1.y; x[6] = s1.z; x[7] = s1.w; }
;         else {
; #pragma unroll
;             for (int e = 0; e < 8; ++e) x[e] = 0.f; }
;         *(LAS v4u*)(HALO + hr * 136 + 8 * cg) = pack8(x); }
;     v4u xr0, xr1; unsigned short zc[16], zn[16];
;     const bf16* xsrc = XA + (rowbase + ct) * DM + c0; const bf16* zsrc = ZA + (rowbase + 4 * tq) * DM + dg;
;     xr0 = *(const GAS v4u*)(xsrc); xr1 = *(const GAS v4u*)(xsrc + (size_t)32 * DM);
; #pragma unroll
;     for (int i = 0; i < 16; ++i) zc[i] = *(const GAS unsigned short*)(zsrc + (size_t)(16 * (i >> 2) + (i & 3)) * DM);
	v_addc_co_u32_e32 v87, vcc, 0, v119, vcc
	v_add_co_u32_e32 v92, vcc, s0, v118
	global_load_dwordx4 v[74:77], v[116:117], off
	global_load_ushort v176, v[118:119], off
	global_load_ushort v173, v[118:119], off offset:2048
	v_addc_co_u32_e32 v93, vcc, 0, v119, vcc
	v_add_co_u32_e32 v94, vcc, s60, v118
	global_load_dwordx4 v[78:81], v[78:79], off
	s_nop 0
	global_load_ushort v177, v[86:87], off
	global_load_ushort v174, v[86:87], off offset:2048
	global_load_ushort v167, v[92:93], off offset:2048
	v_addc_co_u32_e32 v95, vcc, 0, v119, vcc
	v_add_co_u32_e32 v86, vcc, s57, v118
	v_add_f32_e32 v106, v102, v104
	s_nop 0
	v_addc_co_u32_e32 v87, vcc, 0, v119, vcc
	v_add_co_u32_e32 v92, vcc, s61, v118
	v_sub_f32_e32 v107, v106, v102
	s_nop 0
	v_addc_co_u32_e32 v93, vcc, 0, v119, vcc
	v_add_co_u32_e32 v96, vcc, s66, v118
	v_sub_f32_e32 v108, v106, v107
	s_nop 0
	v_addc_co_u32_e32 v97, vcc, 0, v119, vcc
	v_add_co_u32_e32 v98, vcc, s67, v118
	v_sub_f32_e32 v85, v102, v108
	s_nop 0
	v_addc_co_u32_e32 v99, vcc, 0, v119, vcc
	global_load_ushort v178, v[94:95], off offset:-4096
	global_load_ushort v175, v[94:95], off
	global_load_ushort v172, v[94:95], off offset:2048
	global_load_ushort v168, v[92:93], off offset:-4096
	global_load_ushort v166, v[86:87], off offset:2048
	global_load_ushort v165, v[92:93], off
	global_load_ushort v161, v[92:93], off offset:2048
	global_load_ushort v154, v[96:97], off offset:2048
	global_load_ushort v159, v[98:99], off offset:-4096
	global_load_ushort v152, v[98:99], off
	global_load_ushort v150, v[98:99], off offset:2048
	v_sub_f32_e32 v86, v104, v107
	v_add_f32_e32 v85, v86, v85
	v_add_f32_e32 v86, v103, v105
	v_sub_f32_e32 v87, v86, v103
	v_sub_f32_e32 v92, v86, v87
	v_add_f32_e32 v85, v86, v85
	v_sub_f32_e32 v92, v103, v92
	v_sub_f32_e32 v87, v105, v87
	v_add_f32_e32 v86, v106, v85
	v_add_f32_e32 v87, v87, v92
	v_sub_f32_e32 v92, v86, v106
	v_sub_f32_e32 v85, v85, v92
	v_add_f32_e32 v85, v87, v85
	v_add_f32_e32 v85, v86, v85
	v_cmp_neq_f32_e32 vcc, s35, v101
	v_add_u32_e32 v86, 0, v145
	v_lshl_add_u32 v92, v82, 2, 0
	v_cndmask_b32_e32 v85, v127, v85, vcc
	v_cmp_lt_f32_e64 vcc, |v101|, s56
	v_add_u32_e32 v82, 0, v151
	s_and_b32 s0, s86, 7
	v_cndmask_b32_e32 v85, v85, v101, vcc
	v_add_f32_e32 v85, v100, v85
	v_mul_f32_e32 v147, 0xc138aa3b, v85
	v_lshlrev_b32_e32 v85, 1, v90
	v_cmp_lt_i32_e32 vcc, 2, v84
	v_add3_u32 v148, 0, v83, v85
	s_lshl_b32 s2, s0, 7
	v_cndmask_b32_e32 v83, v128, v129, vcc
	v_cmp_lt_i32_e32 vcc, 1, v84
	v_add3_u32 v153, v86, v83, v85
	s_lshl_b64 s[0:1], s[44:45], 12
	v_cndmask_b32_e32 v83, v130, v131, vcc
	v_cmp_lt_i32_e32 vcc, 0, v84
	v_add3_u32 v155, v86, v83, v85
	v_lshl_add_u32 v87, v90, 2, 0
	v_cndmask_b32_e32 v83, v132, v133, vcc
	v_cmp_gt_i32_e32 vcc, 0, v84
	v_add3_u32 v156, v86, v83, v85
	v_sub_u32_e32 v149, v87, v85
	v_cndmask_b32_e32 v83, v134, v135, vcc
	v_cmp_lt_i32_e32 vcc, s69, v84
	v_add3_u32 v157, v86, v83, v85
	v_mul_lo_u32 v93, v84, s68
	v_cndmask_b32_e32 v83, v128, v129, vcc
	v_cmp_lt_i32_e32 vcc, s70, v84
	v_add3_u32 v158, v82, v83, v85
	v_mov_b32_e32 v83, v115
	v_cndmask_b32_e32 v82, v136, v137, vcc
	v_cmp_lt_i32_e32 vcc, s71, v84
	v_add3_u32 v160, v86, v82, v85
	v_lshl_add_u32 v90, v91, 4, 0
	v_cndmask_b32_e32 v82, v138, v139, vcc
	v_cmp_lt_i32_e32 vcc, s76, v84
	v_add3_u32 v162, v86, v82, v85
	v_cmp_lt_u32_e64 s[6:7], 1, v91
	v_cndmask_b32_e32 v82, v140, v141, vcc
	v_add3_u32 v163, v86, v82, v85
	v_or_b32_e32 v82, v89, v121
	v_lshl_or_b32 v164, v82, 2, v142
	v_lshlrev_b32_e32 v82, 8, v88
	v_and_b32_e32 v120, 0x3000, v82
	v_lshlrev_b32_e32 v82, 10, v88
	v_and_b32_e32 v82, 0xc000, v82
	v_lshl_add_u64 v[82:83], v[82:83], 0, s[0:1]
	s_add_i32 s0, s3, s2
	v_add_u32_e32 v84, s0, v89
	v_mov_b32_e32 v85, v115
	v_mul_u32_u24_e32 v94, 0x110, v89
	v_mul_u32_u24_e32 v91, 0x840, v91
	v_lshl_add_u64 v[82:83], v[84:85], 1, v[82:83]
	s_mov_b32 s37, 0
	v_lshl_add_u64 v[122:123], s[74:75], 0, v[82:83]
	s_mov_b64 s[0:1], 0
	v_add_u32_e32 v169, v87, v93
	v_add_u32_e32 v170, v90, v94
	v_add_u32_e32 v171, v92, v91

; #define LAS __attribute__((address_space(3)))
; __device__ __forceinline__ float sigm(float v) { return __builtin_amdgcn_rcpf(1.f + __builtin_amdgcn_exp2f(-LOG2E * v)); }
; __device__ __forceinline__ void lru_unit(Frame& F, int seq, int n) {
;     ...
;             for (int tt = 0; tt < 4; ++tt)
; #pragma unroll
;                 for (int kk = 0; kk < 4; ++kk) {
;                     const bf16x8 af = *(const LAS bf16x8*)(XCB + (16 * tt + (lane & 15)) * 136 + 32 * kk + 8 * tq);
;                     ar[tt] = __builtin_amdgcn_mfma_f32_16x16x32_bf16(af, Br[kk], ar[tt], 0, 0, 0);
;                     ai_[tt] = __builtin_amdgcn_mfma_f32_16x16x32_bf16(af, Bi[kk], ai_[tt], 0, 0, 0);
;                 }
;             float A[4][4], B[4][4];
; #pragma unroll
;             for (int tt = 0; tt < 4; ++tt)
; #pragma unroll
;                 for (int rg = 0; rg < 4; ++rg) {
;                     const int t = 16 * tt + 4 * tq + rg;
;                     const float r = sigm(ar[tt][rg] + brg), ig = sigm(ai_[tt][rg] + big);
;                     const float av = __builtin_amdgcn_exp2f(r * nsp);
;                     float mult = __builtin_amdgcn_sqrtf(fmaxf(__builtin_fmaf(-av, av, 1.f), 0.f));
;                     if (!smp && (t0 + t) == 0) mult = 1.f;
;                     A[tt][rg] = av; B[tt][rg] = mult * ig * BB[t * 132 + dl];
.LBB0_440:
	s_or_b64 exec, exec, s[46:47]
	s_waitcnt lgkmcnt(0)
	s_barrier
	ds_read_b128 v[82:85], v170
	ds_read_b128 v[90:93], v170 offset:64
	s_waitcnt lgkmcnt(1)
	v_mfma_f32_16x16x32_bf16 v[86:89], v[82:85], v[42:45], 0
	ds_read_b128 v[196:199], v170 offset:13120
	v_mfma_f32_16x16x32_bf16 v[82:85], v[82:85], v[66:69], 0
	s_waitcnt lgkmcnt(1)
	v_mfma_f32_16x16x32_bf16 v[86:89], v[90:93], v[46:49], v[86:89]
	v_mfma_f32_16x16x32_bf16 v[82:85], v[90:93], v[50:53], v[82:85]
	ds_read_b128 v[90:93], v170 offset:128
	s_waitcnt lgkmcnt(0)
	v_mfma_f32_16x16x32_bf16 v[86:89], v[90:93], v[58:61], v[86:89]
	v_mfma_f32_16x16x32_bf16 v[82:85], v[90:93], v[54:57], v[82:85]
	ds_read_b128 v[90:93], v170 offset:192
	s_waitcnt lgkmcnt(0)
	v_mfma_f32_16x16x32_bf16 v[106:109], v[90:93], v[70:73], v[82:85]
	s_nop 4
	ds_read_b128 v[82:85], v170 offset:4352
	s_nop 1
	v_fma_f32 v106, v106, s90, v144
	v_mfma_f32_16x16x32_bf16 v[110:113], v[90:93], v[62:65], v[86:89]
	ds_read_b128 v[90:93], v170 offset:4416
	s_nop 0
	v_exp_f32_e32 v106, v106
	s_waitcnt lgkmcnt(1)
	v_mfma_f32_16x16x32_bf16 v[86:89], v[82:85], v[42:45], 0
	v_fma_f32 v107, v107, s90, v144
	s_nop 1
	v_fma_f32 v110, v110, s90, v143
	s_nop 0
	v_mfma_f32_16x16x32_bf16 v[82:85], v[82:85], v[66:69], 0
	v_exp_f32_e32 v110, v110
	v_add_f32_e32 v106, 1.0, v106
	v_rcp_f32_e32 v106, v106
	s_waitcnt lgkmcnt(0)
	v_mfma_f32_16x16x32_bf16 v[86:89], v[90:93], v[46:49], v[86:89]
	v_add_f32_e32 v110, 1.0, v110
	v_rcp_f32_e32 v110, v110
	s_nop 0
	v_mfma_f32_16x16x32_bf16 v[82:85], v[90:93], v[50:53], v[82:85]
	ds_read_b128 v[90:93], v170 offset:4480
	v_mul_f32_e32 v110, v147, v110
	v_exp_f32_e32 v110, v110
	s_waitcnt lgkmcnt(0)
	v_mfma_f32_16x16x32_bf16 v[86:89], v[90:93], v[58:61], v[86:89]
	v_fma_f32 v195, -v110, v110, 1.0 clamp
	s_nop 0
	v_sqrt_f32_e32 v195, v195
	v_mfma_f32_16x16x32_bf16 v[82:85], v[90:93], v[54:57], v[82:85]
	ds_read_b128 v[90:93], v170 offset:4544
	v_exp_f32_e32 v107, v107
	v_fma_f32 v109, v109, s90, v144
	s_waitcnt lgkmcnt(0)
	v_mfma_f32_16x16x32_bf16 v[98:101], v[90:93], v[70:73], v[82:85]
	s_nop 2
	ds_read_b128 v[82:85], v170 offset:8704
	v_add_f32_e32 v107, 1.0, v107
	v_rcp_f32_e32 v107, v107
	v_mfma_f32_16x16x32_bf16 v[102:105], v[90:93], v[62:65], v[86:89]
	ds_read_b128 v[90:93], v170 offset:8768
	s_nop 0
	v_exp_f32_e32 v109, v109
	s_waitcnt lgkmcnt(1)
	v_mfma_f32_16x16x32_bf16 v[86:89], v[82:85], v[42:45], 0
	v_add_f32_e32 v109, 1.0, v109
	s_nop 1
	v_fma_f32 v102, v102, s90, v143
	s_nop 0
	v_mfma_f32_16x16x32_bf16 v[82:85], v[82:85], v[66:69], 0
	v_exp_f32_e32 v102, v102
	v_rcp_f32_e32 v109, v109
	v_fma_f32 v98, v98, s90, v144
	s_waitcnt lgkmcnt(0)
	v_mfma_f32_16x16x32_bf16 v[86:89], v[90:93], v[46:49], v[86:89]
	v_add_f32_e32 v102, 1.0, v102
	v_rcp_f32_e32 v102, v102
	s_nop 0
	v_mfma_f32_16x16x32_bf16 v[82:85], v[90:93], v[50:53], v[82:85]
	ds_read_b128 v[90:93], v170 offset:8832
	v_mul_f32_e32 v102, v147, v102
	v_exp_f32_e32 v98, v98
	s_waitcnt lgkmcnt(0)
	v_mfma_f32_16x16x32_bf16 v[86:89], v[90:93], v[58:61], v[86:89]
	v_add_f32_e32 v98, 1.0, v98
	v_rcp_f32_e32 v98, v98
	v_fma_f32 v99, v99, s90, v144
	v_mfma_f32_16x16x32_bf16 v[82:85], v[90:93], v[54:57], v[82:85]
	ds_read_b128 v[90:93], v170 offset:8896
	s_nop 0
	v_exp_f32_e32 v99, v99
	s_waitcnt lgkmcnt(0)
	v_mfma_f32_16x16x32_bf16 v[94:97], v[90:93], v[62:65], v[86:89]
	v_add_f32_e32 v99, 1.0, v99
	v_rcp_f32_e32 v99, v99
	v_fma_f32 v101, v101, s90, v144
	v_mfma_f32_16x16x32_bf16 v[90:93], v[90:93], v[70:73], v[82:85]
	s_nop 3
	v_fma_f32 v94, v94, s90, v143
	s_nop 0
	v_exp_f32_e32 v94, v94
	ds_read_b128 v[82:85], v170 offset:13056
	s_waitcnt lgkmcnt(0)
	v_mfma_f32_16x16x32_bf16 v[86:89], v[82:85], v[42:45], 0
	v_add_f32_e32 v94, 1.0, v94
	v_rcp_f32_e32 v94, v94
	v_fma_f32 v90, v90, s90, v144
	v_mfma_f32_16x16x32_bf16 v[82:85], v[82:85], v[66:69], 0
	s_nop 0
	v_mul_f32_e32 v94, v147, v94
	v_exp_f32_e32 v90, v90
	v_mfma_f32_16x16x32_bf16 v[86:89], v[196:199], v[46:49], v[86:89]
	s_nop 0
	v_exp_f32_e32 v101, v101
	v_add_f32_e32 v90, 1.0, v90
	v_mfma_f32_16x16x32_bf16 v[82:85], v[196:199], v[50:53], v[82:85]
	ds_read_b128 v[196:199], v170 offset:13184
	v_rcp_f32_e32 v90, v90
	v_add_f32_e32 v101, 1.0, v101
	s_waitcnt lgkmcnt(0)
	v_mfma_f32_16x16x32_bf16 v[86:89], v[196:199], v[58:61], v[86:89]
	v_rcp_f32_e32 v206, v101
	v_fma_f32 v91, v91, s90, v144
	s_nop 0
	v_mfma_f32_16x16x32_bf16 v[82:85], v[196:199], v[54:57], v[82:85]
	ds_read_b128 v[196:199], v170 offset:13248
	v_exp_f32_e32 v91, v91
	v_fma_f32 v93, v93, s90, v144
	s_waitcnt lgkmcnt(0)
	v_mfma_f32_16x16x32_bf16 v[86:89], v[196:199], v[62:65], v[86:89]
	v_add_f32_e32 v91, 1.0, v91
	v_rcp_f32_e32 v91, v91
	s_nop 0
	v_mfma_f32_16x16x32_bf16 v[82:85], v[196:199], v[70:73], v[82:85]
	v_add_u32_e32 v196, s0, v120
	v_cmp_eq_u32_e32 vcc, 0, v196
	s_and_b64 s[46:47], s[40:41], vcc
	v_cndmask_b32_e64 v195, v195, 1.0, s[46:47]
	v_mul_f32_e32 v106, v106, v195
	v_add_u32_e32 v195, 0x8c00, v171
	ds_read2_b32 v[196:197], v195 offset1:132
	v_fma_f32 v86, v86, s90, v143
	s_nop 0
	v_exp_f32_e32 v86, v86
	v_fma_f32 v82, v82, s90, v144
	s_waitcnt lgkmcnt(0)
; __device__ __forceinline__ float sigm(float v) { return __builtin_amdgcn_rcpf(1.f + __builtin_amdgcn_exp2f(-LOG2E * v)); }
; __device__ __forceinline__ void lru_unit(Frame& F, int seq, int n) {
;     ...
;             for (int tt = 0; tt < 4; ++tt)
; #pragma unroll
;                 for (int rg = 0; rg < 4; ++rg) {
;                     const int t = 16 * tt + 4 * tq + rg;
;                     const float r = sigm(ar[tt][rg] + brg), ig = sigm(ai_[tt][rg] + big);
;                     const float av = __builtin_amdgcn_exp2f(r * nsp);
;                     float mult = __builtin_amdgcn_sqrtf(fmaxf(__builtin_fmaf(-av, av, 1.f), 0.f));
;                     if (!smp && (t0 + t) == 0) mult = 1.f;
;                     A[tt][rg] = av; B[tt][rg] = mult * ig * BB[t * 132 + dl];
;                 }
; #pragma unroll
;             for (int tt = 0; tt < 4; ++tt)
; #pragma unroll
;                 for (int rg = 1; rg < 4; ++rg) { B[tt][rg] = A[tt][rg] * B[tt][rg - 1] + B[tt][rg]; A[tt][rg] = A[tt][rg] * A[tt][rg - 1]; }
	v_mul_f32_e32 v195, v106, v196
	v_fma_f32 v106, v111, s90, v143
	s_nop 0
	v_exp_f32_e32 v106, v106
	v_add_f32_e32 v86, 1.0, v86
	v_rcp_f32_e32 v86, v86
	s_nop 0
	v_add_f32_e32 v106, 1.0, v106
	v_rcp_f32_e32 v106, v106
	v_mul_f32_e32 v86, v147, v86
	v_exp_f32_e32 v82, v82
	v_fma_f32 v83, v83, s90, v144
	v_mul_f32_e32 v106, v147, v106
	v_exp_f32_e32 v196, v106
	v_add_f32_e32 v82, 1.0, v82
	v_rcp_f32_e32 v82, v82
	s_nop 0
	v_fma_f32 v106, -v196, v196, 1.0 clamp
	s_nop 0
	v_sqrt_f32_e32 v106, v106
	v_exp_f32_e32 v83, v83
	v_exp_f32_e32 v93, v93
	v_fma_f32 v92, v92, s90, v144
	v_mul_f32_e32 v106, v107, v106
	v_fma_f32 v107, v108, s90, v144
	v_fma_f32 v108, v113, s90, v143
	s_nop 0
	v_exp_f32_e32 v108, v108
	v_mul_f32_e32 v111, v106, v197
	v_fma_f32 v106, v112, s90, v143
	s_nop 0
	v_add_f32_e32 v108, 1.0, v108
	v_rcp_f32_e32 v108, v108
	v_exp_f32_e32 v106, v106
	s_nop 0
	v_exp_f32_e32 v107, v107
	v_mul_f32_e32 v108, v147, v108
	v_exp_f32_e32 v199, v108
	v_add_f32_e32 v106, 1.0, v106
	v_rcp_f32_e32 v106, v106
	v_add_f32_e32 v83, 1.0, v83
	v_fma_f32 v108, -v199, v199, 1.0 clamp
	s_nop 0
	v_sqrt_f32_e32 v108, v108
	v_mul_f32_e32 v106, v147, v106
	v_exp_f32_e32 v197, v106
	v_add_f32_e32 v107, 1.0, v107
	v_mul_f32_e32 v200, v109, v108
	v_exp_f32_e32 v108, v102
	v_fma_f32 v106, -v197, v197, 1.0 clamp
	s_nop 0
	v_rcp_f32_e32 v107, v107
	v_fma_f32 v102, -v108, v108, 1.0 clamp
	s_nop 0
	v_sqrt_f32_e32 v102, v102
	v_sqrt_f32_e32 v106, v106
	v_fmac_f32_e32 v111, v196, v195
	s_nop 0
	v_mul_f32_e32 v98, v98, v102
	v_add_u32_e32 v102, 0xac00, v171
	ds_read2_b32 v[112:113], v102 offset0:64 offset1:196
	v_fma_f32 v102, v105, s90, v143
	s_nop 0
	v_exp_f32_e32 v102, v102
	v_mul_f32_e32 v198, v107, v106
	s_waitcnt lgkmcnt(0)
	v_mul_f32_e32 v109, v98, v112
	v_fma_f32 v98, v103, s90, v143
	s_nop 0
	v_exp_f32_e32 v98, v98
	v_add_f32_e32 v102, 1.0, v102
	v_rcp_f32_e32 v102, v102
	v_add_u32_e32 v106, 0x9000, v171
	v_add_f32_e32 v98, 1.0, v98
	v_rcp_f32_e32 v98, v98
	v_mul_f32_e32 v101, v147, v102
	v_exp_f32_e32 v101, v101
	ds_read2_b32 v[106:107], v106 offset0:8 offset1:140
	v_mul_f32_e32 v98, v147, v98
	v_exp_f32_e32 v203, v98
	v_add_f32_e32 v93, 1.0, v93
	v_mul_f32_e32 v201, v197, v111
	v_exp_f32_e32 v92, v92
	v_fma_f32 v98, -v203, v203, 1.0 clamp
	s_nop 0
	v_sqrt_f32_e32 v98, v98
	v_rcp_f32_e32 v210, v93
	s_waitcnt lgkmcnt(0)
	v_fmac_f32_e32 v201, v198, v106
	v_mul_f32_e32 v106, v203, v108
	v_mul_f32_e32 v98, v99, v98
	v_mul_f32_e32 v112, v98, v113
	v_fma_f32 v98, v104, s90, v143
	v_exp_f32_e32 v104, v94
	v_exp_f32_e32 v113, v86
	s_nop 0
	v_exp_f32_e32 v98, v98
	v_fma_f32 v94, -v104, v104, 1.0 clamp
	s_nop 0
	v_sqrt_f32_e32 v94, v94
	v_fma_f32 v86, -v113, v113, 1.0 clamp
	s_nop 0
	v_sqrt_f32_e32 v86, v86
	v_mul_f32_e32 v90, v90, v94
	v_add_u32_e32 v94, 0xce00, v171
	ds_read2_b32 v[102:103], v94 offset1:132
	v_mul_f32_e32 v86, v82, v86
	v_add_u32_e32 v82, 0xee00, v171
	v_add_f32_e32 v98, 1.0, v98
	v_rcp_f32_e32 v98, v98
	s_waitcnt lgkmcnt(0)
	v_mul_f32_e32 v105, v90, v102
	v_fma_f32 v90, v95, s90, v143
	s_nop 0
	v_exp_f32_e32 v90, v90
	v_fma_f32 v99, v100, s90, v144
	v_mul_f32_e32 v98, v147, v98
	s_nop 0
	v_add_f32_e32 v90, 1.0, v90
	v_rcp_f32_e32 v90, v90
	v_exp_f32_e32 v100, v98
	v_exp_f32_e32 v99, v99
	v_fmac_f32_e32 v112, v203, v109
	v_mul_f32_e32 v90, v147, v90
	v_exp_f32_e32 v90, v90
	v_fma_f32 v98, -v100, v100, 1.0 clamp
	v_add_f32_e32 v99, 1.0, v99
	s_nop 0
	v_fma_f32 v94, -v90, v90, 1.0 clamp
	s_nop 0
	v_sqrt_f32_e32 v94, v94
	v_rcp_f32_e32 v99, v99
	v_sqrt_f32_e32 v98, v98
	v_add_f32_e32 v92, 1.0, v92
	v_mul_f32_e32 v91, v91, v94
	v_fma_f32 v94, v96, s90, v143
	s_nop 0
	v_exp_f32_e32 v94, v94
	v_mul_f32_e32 v91, v91, v103
	v_mul_f32_e32 v205, v99, v98
	v_add_u32_e32 v98, 0xb000, v171
	v_add_f32_e32 v94, 1.0, v94
	v_rcp_f32_e32 v94, v94
	ds_read2_b32 v[98:99], v98 offset0:72 offset1:204
	v_rcp_f32_e32 v92, v92
	v_fmac_f32_e32 v91, v90, v105
	v_mul_f32_e32 v94, v147, v94
	v_exp_f32_e32 v95, v94
	v_add_u32_e32 v94, 0xd200, v171
	ds_read2_b32 v[102:103], v94 offset0:8 offset1:140
	v_fma_f32 v94, v97, s90, v143
	ds_read2_b32 v[96:97], v82 offset0:64 offset1:196
	v_fma_f32 v82, v87, s90, v143
	s_nop 0
	v_exp_f32_e32 v82, v82
	v_rcp_f32_e32 v87, v83
	v_fma_f32 v83, v84, s90, v144
	s_nop 0
	v_add_f32_e32 v82, 1.0, v82
	v_rcp_f32_e32 v82, v82
	v_exp_f32_e32 v83, v83
	s_nop 0
	v_exp_f32_e32 v94, v94
	v_mul_f32_e32 v82, v147, v82
	v_exp_f32_e32 v204, v82
	v_fma_f32 v82, v88, s90, v143
	s_nop 0
	v_exp_f32_e32 v82, v82
	v_add_f32_e32 v83, 1.0, v83
	v_rcp_f32_e32 v214, v83
	v_fma_f32 v83, v85, s90, v144
	v_add_f32_e32 v82, 1.0, v82
	v_rcp_f32_e32 v82, v82
	s_nop 0
	v_add_f32_e32 v94, 1.0, v94
	v_exp_f32_e32 v83, v83
	v_mul_f32_e32 v82, v147, v82
	v_exp_f32_e32 v207, v82
	v_add_u32_e32 v82, 0xf200, v171
	ds_read2_b32 v[208:209], v82 offset0:72 offset1:204
	v_fma_f32 v82, v89, s90, v143
	s_nop 0
	v_exp_f32_e32 v82, v82
	v_rcp_f32_e32 v94, v94
	v_add_f32_e32 v83, 1.0, v83
	v_rcp_f32_e32 v215, v83
	v_add_f32_e32 v82, 1.0, v82
	v_rcp_f32_e32 v82, v82
	v_mul_f32_e32 v93, v147, v94
	v_mul_f32_e32 v83, v100, v112
	v_exp_f32_e32 v93, v93
	v_mul_f32_e32 v82, v147, v82
	v_exp_f32_e32 v211, v82
	v_fma_f32 v82, -v101, v101, 1.0 clamp
	s_nop 0
	v_sqrt_f32_e32 v82, v82
	s_waitcnt lgkmcnt(3)
	v_fmac_f32_e32 v83, v205, v98
	v_mul_f32_e32 v98, v100, v106
	v_mov_b32_e32 v100, v99
	v_mul_f32_e32 v82, v206, v82
	v_pk_mul_f32 v[84:85], v[82:83], v[100:101]
	v_fma_f32 v88, -v93, v93, 1.0 clamp
	v_add_f32_e32 v99, v84, v85
	v_fma_f32 v84, -v95, v95, 1.0 clamp
	s_nop 0
	v_sqrt_f32_e32 v84, v84
	s_nop 0
	v_sqrt_f32_e32 v88, v88
	v_mul_f32_e32 v82, v90, v104
	s_waitcnt lgkmcnt(2)
; __device__ __forceinline__ void lru_unit(Frame& F, int seq, int n) {
;     ...
;                     float mult = __builtin_amdgcn_sqrtf(fmaxf(__builtin_fmaf(-av, av, 1.f), 0.f));
;                     if (!smp && (t0 + t) == 0) mult = 1.f;
;                     A[tt][rg] = av; B[tt][rg] = mult * ig * BB[t * 132 + dl];
;                 }
; #pragma unroll
;             for (int tt = 0; tt < 4; ++tt)
; #pragma unroll
;                 for (int rg = 1; rg < 4; ++rg) { B[tt][rg] = A[tt][rg] * B[tt][rg - 1] + B[tt][rg]; A[tt][rg] = A[tt][rg] * A[tt][rg - 1]; }
;             float EA[4], EB[4], TA[4], TB[4];
; #pragma unroll
;             for (int tt = 0; tt < 4; ++tt) {
;                 float SA = A[tt][3], SB = B[tt][3];
;                 { const float pA = __shfl_up(SA, 16), pB = __shfl_up(SB, 16); if (tq >= 1) { SB = SA * pB + SB; SA = SA * pA; } }
;                 { const float pA = __shfl_up(SA, 32), pB = __shfl_up(SB, 32); if (tq >= 2) { SB = SA * pB + SB; SA = SA * pA; } }
;                 { const float pA = __shfl_up(SA, 16), pB = __shfl_up(SB, 16); EA[tt] = (tq >= 1) ? pA : 1.f; EB[tt] = (tq >= 1) ? pB : 0.f; }
;                 TA[tt] = __shfl(SA, (lane & 15) + 48); TB[tt] = __shfl(SB, (lane & 15) + 48);
;             }
	v_mov_b32_e32 v94, v102
	v_mul_f32_e32 v90, v92, v84
	v_mul_f32_e32 v84, v91, v95
	v_pk_fma_f32 v[84:85], v[90:91], v[94:95], v[84:85] op_sel_hi:[1,1,0]
	v_mov_b32_e32 v92, v103
	v_mul_f32_e32 v88, v210, v88
	v_mov_b32_e32 v89, v84
	v_pk_mul_f32 v[88:89], v[88:89], v[92:93]
	s_waitcnt lgkmcnt(1)
	v_mov_b32_e32 v205, v97
	v_add_f32_e32 v90, v88, v89
	v_fma_f32 v88, -v204, v204, 1.0 clamp
	s_nop 0
	v_sqrt_f32_e32 v89, v88
	v_mov_b32_e32 v88, v96
	v_mul_f32_e32 v85, v95, v82
	v_mul_f32_e32 v94, v93, v85
	v_pk_mul_f32 v[88:89], v[86:87], v[88:89]
	s_waitcnt lgkmcnt(0)
	v_mov_b32_e32 v206, v208
	v_mul_f32_e32 v86, v97, v89
	v_pk_fma_f32 v[86:87], v[204:205], v[88:89], v[86:87] op_sel_hi:[1,1,0]
	v_fma_f32 v89, -v207, v207, 1.0 clamp
	s_nop 0
	v_sqrt_f32_e32 v89, v89
	v_mov_b32_e32 v93, v86
	v_mul_f32_e32 v96, v86, v207
	v_mul_f32_e32 v202, v196, v110
	v_mul_f32_e32 v92, v214, v89
	v_pk_fma_f32 v[92:93], v[92:93], v[206:207], v[96:97] op_sel_hi:[1,1,0]
	v_mul_f32_e32 v197, v197, v202
	v_fma_f32 v93, -v211, v211, 1.0 clamp
	s_nop 0
	v_sqrt_f32_e32 v93, v93
	v_mul_f32_e32 v196, v199, v201
	v_mov_b32_e32 v210, v209
	v_mov_b32_e32 v97, v92
	v_mul_f32_e32 v96, v215, v93
	v_fmac_f32_e32 v196, v200, v107
	v_mul_f32_e32 v107, v199, v197
	v_pk_mul_f32 v[96:97], v[96:97], v[210:211]
	v_mul_f32_e32 v100, v101, v98
	v_add_f32_e32 v93, v96, v97
	ds_bpermute_b32 v96, v124, v107
	ds_bpermute_b32 v97, v124, v196
	v_mul_f32_e32 v87, v204, v113
	v_mul_f32_e32 v89, v207, v87
	v_mul_f32_e32 v95, v211, v89
	s_waitcnt lgkmcnt(1)
	v_mul_f32_e32 v96, v107, v96
	s_waitcnt lgkmcnt(0)
	v_fma_f32 v97, v107, v97, v196
	v_cndmask_b32_e64 v96, v96, v107, s[4:5]
	v_cndmask_b32_e64 v97, v97, v196, s[4:5]
	ds_bpermute_b32 v101, v125, v96
	ds_bpermute_b32 v102, v125, v97
	s_waitcnt lgkmcnt(1)
	v_mul_f32_e32 v101, v96, v101
	s_waitcnt lgkmcnt(0)
	v_fma_f32 v102, v96, v102, v97
	v_cndmask_b32_e64 v96, v96, v101, s[6:7]
	v_cndmask_b32_e64 v97, v97, v102, s[6:7]
	ds_bpermute_b32 v101, v124, v96
	ds_bpermute_b32 v199, v164, v96
	ds_bpermute_b32 v96, v124, v100
	ds_bpermute_b32 v102, v124, v97
	ds_bpermute_b32 v200, v164, v97
	ds_bpermute_b32 v97, v124, v99
	s_waitcnt lgkmcnt(5)
	v_cndmask_b32_e64 v101, v101, 1.0, s[4:5]
	s_waitcnt lgkmcnt(3)
	v_mul_f32_e32 v96, v100, v96
	v_cndmask_b32_e64 v96, v96, v100, s[4:5]
	s_waitcnt lgkmcnt(2)
	v_cndmask_b32_e64 v198, v102, 0, s[4:5]
	s_waitcnt lgkmcnt(0)
	v_fma_f32 v97, v100, v97, v99
	v_cndmask_b32_e64 v97, v97, v99, s[4:5]
	ds_bpermute_b32 v102, v125, v96
	ds_bpermute_b32 v103, v125, v97
	v_fmac_f32_e32 v198, v146, v101
	v_fmac_f32_e32 v195, v110, v198
	v_fmac_f32_e32 v111, v202, v198
	s_waitcnt lgkmcnt(1)
	v_mul_f32_e32 v102, v96, v102
	s_waitcnt lgkmcnt(0)
	v_fma_f32 v103, v96, v103, v97
	v_cndmask_b32_e64 v96, v96, v102, s[6:7]
	v_cndmask_b32_e64 v97, v97, v103, s[6:7]
	ds_bpermute_b32 v102, v124, v96
	ds_bpermute_b32 v205, v164, v96
	ds_bpermute_b32 v96, v124, v94
	ds_bpermute_b32 v103, v124, v97
	ds_bpermute_b32 v206, v164, v97
	ds_bpermute_b32 v97, v124, v90
	s_waitcnt lgkmcnt(5)
	v_cndmask_b32_e64 v203, v102, 1.0, s[4:5]
	s_waitcnt lgkmcnt(3)
	v_mul_f32_e32 v96, v94, v96
	v_cndmask_b32_e64 v96, v96, v94, s[4:5]
	ds_bpermute_b32 v102, v125, v96
	s_waitcnt lgkmcnt(1)
	v_fma_f32 v97, v94, v97, v90
	v_cndmask_b32_e64 v97, v97, v90, s[4:5]
	v_cndmask_b32_e64 v204, v103, 0, s[4:5]
	ds_bpermute_b32 v103, v125, v97
	s_waitcnt lgkmcnt(1)
	v_mul_f32_e32 v102, v96, v102
	v_fmac_f32_e32 v201, v197, v198
	v_fmac_f32_e32 v196, v107, v198
	v_fmac_f32_e32 v200, v146, v199
	s_waitcnt lgkmcnt(0)
	v_fma_f32 v103, v96, v103, v97
	v_cndmask_b32_e64 v96, v96, v102, s[6:7]
	v_cndmask_b32_e64 v97, v97, v103, s[6:7]
	ds_bpermute_b32 v102, v124, v96
	ds_bpermute_b32 v209, v164, v96
	ds_bpermute_b32 v96, v124, v95
	ds_bpermute_b32 v103, v124, v97
	ds_bpermute_b32 v210, v164, v97
	ds_bpermute_b32 v97, v124, v93
	s_waitcnt lgkmcnt(5)
	v_cndmask_b32_e64 v207, v102, 1.0, s[4:5]
	s_waitcnt lgkmcnt(3)
	v_mul_f32_e32 v96, v95, v96
	v_cndmask_b32_e64 v96, v96, v95, s[4:5]
	ds_bpermute_b32 v102, v125, v96
	s_waitcnt lgkmcnt(1)
	v_fma_f32 v97, v95, v97, v93
	v_cndmask_b32_e64 v97, v97, v93, s[4:5]
	v_cndmask_b32_e64 v208, v103, 0, s[4:5]
	ds_bpermute_b32 v103, v125, v97
	s_waitcnt lgkmcnt(1)
	v_mul_f32_e32 v102, v96, v102
	v_fmac_f32_e32 v204, v200, v203
	v_fmac_f32_e32 v109, v108, v204
	v_fmac_f32_e32 v112, v106, v204
	s_waitcnt lgkmcnt(0)
	v_fma_f32 v103, v96, v103, v97
	v_cndmask_b32_e64 v96, v96, v102, s[6:7]
	v_cndmask_b32_e64 v97, v97, v103, s[6:7]
	ds_bpermute_b32 v102, v124, v96
	ds_bpermute_b32 v103, v124, v97
	ds_bpermute_b32 v215, v164, v96
	v_lshlrev_b32_e32 v96, 16, v176
	v_mul_f32_e32 v96, v195, v96
	ds_bpermute_b32 v216, v164, v97
	v_cvt_pk_bf16_f32 v101, v96, v115
	v_lshl_add_u64 v[96:97], v[122:123], 0, s[0:1]
	s_waitcnt lgkmcnt(3)
; #define GAS __attribute__((address_space(1)))
; __device__ __forceinline__ unsigned pk2(float lo, float hi) { return pg8::cvt_pk_bf16(lo, hi); }
; __device__ __forceinline__ void lru_unit(Frame& F, int seq, int n) {
;     ...
;             const size_t r0 = rowbase + t0 + 4 * tq;
; #pragma unroll
;             for (int tt = 0; tt < 4; ++tt) {
;                 const float hin = EA[tt] * hc + EB[tt];
; #pragma unroll
;                 for (int rg = 0; rg < 4; ++rg) { const float h = A[tt][rg] * hin + B[tt][rg];
;                     const float y = h * bf2f(zc[4 * tt + rg]);
;                     *(GAS unsigned short*)(YAB + (r0 + 16 * tt + rg) * (2 * DM) + dg) = (unsigned short)(pk2(y, 0.f) & 0xffffu); }
;                 hc = TA[tt] * hc + TB[tt];
;             }
; #pragma unroll
;             for (int i = 0; i < 16; ++i) zc[i] = zn[i];
	v_cndmask_b32_e64 v211, v102, 1.0, s[4:5]
	v_add_co_u32_e32 v102, vcc, s77, v96
	s_waitcnt lgkmcnt(2)
	v_cndmask_b32_e64 v214, v103, 0, s[4:5]
	v_addc_co_u32_e32 v103, vcc, 0, v97, vcc
	global_store_short v[102:103], v101, off offset:-4096
	v_lshlrev_b32_e32 v101, 16, v173
	v_mul_f32_e32 v101, v111, v101
	v_cvt_pk_bf16_f32 v101, v101, v115
	global_store_short v[102:103], v101, off
	s_waitcnt vmcnt(33)
	v_lshlrev_b32_e32 v101, 16, v177
	v_mul_f32_e32 v101, v201, v101
	v_add_co_u32_e32 v102, vcc, s78, v96
	v_cvt_pk_bf16_f32 v101, v101, v115
	v_fmac_f32_e32 v83, v98, v204
	s_nop 0
	v_addc_co_u32_e32 v103, vcc, 0, v97, vcc
	global_store_short v[102:103], v101, off offset:-4096
	s_waitcnt vmcnt(33)
	v_lshlrev_b32_e32 v101, 16, v174
	v_mul_f32_e32 v101, v196, v101
	v_cvt_pk_bf16_f32 v101, v101, v115
	global_store_short v[102:103], v101, off
	s_waitcnt vmcnt(32)
	v_lshlrev_b32_e32 v101, 16, v178
	v_mul_f32_e32 v101, v109, v101
	v_add_co_u32_e32 v102, vcc, s79, v96
	v_cvt_pk_bf16_f32 v101, v101, v115
	s_waitcnt vmcnt(31)
	v_lshlrev_b32_e32 v98, 16, v175
	v_addc_co_u32_e32 v103, vcc, 0, v97, vcc
	global_store_short v[102:103], v101, off offset:-4096
	v_lshlrev_b32_e32 v101, 16, v167
	v_mul_f32_e32 v101, v112, v101
	v_cvt_pk_bf16_f32 v101, v101, v115
	global_store_short v[102:103], v101, off
	v_mul_f32_e32 v83, v83, v98
	v_add_co_u32_e32 v102, vcc, s80, v96
	v_cvt_pk_bf16_f32 v83, v83, v115
	v_fmac_f32_e32 v99, v100, v204
	s_nop 0
	v_addc_co_u32_e32 v103, vcc, 0, v97, vcc
	global_store_short v[102:103], v83, off offset:-4096
	s_waitcnt vmcnt(33)
	v_lshlrev_b32_e32 v83, 16, v172
	v_mul_f32_e32 v83, v99, v83
	v_fmac_f32_e32 v206, v200, v205
	v_cvt_pk_bf16_f32 v83, v83, v115
	v_fmac_f32_e32 v208, v206, v207
	global_store_short v[102:103], v83, off
	v_fmac_f32_e32 v105, v104, v208
	s_waitcnt vmcnt(33)
	v_lshlrev_b32_e32 v83, 16, v168
	v_add_co_u32_e32 v98, vcc, s81, v96
	v_fmac_f32_e32 v91, v82, v208
	s_waitcnt vmcnt(32)
	v_lshlrev_b32_e32 v82, 16, v166
	v_mul_f32_e32 v83, v105, v83
	v_addc_co_u32_e32 v99, vcc, 0, v97, vcc
	v_mul_f32_e32 v82, v91, v82
	v_cvt_pk_bf16_f32 v83, v83, v115
	global_store_short v[98:99], v83, off offset:-4096
	v_cvt_pk_bf16_f32 v82, v82, v115
	global_store_short v[98:99], v82, off
	v_fmac_f32_e32 v84, v85, v208
	s_waitcnt vmcnt(33)
	v_lshlrev_b32_e32 v82, 16, v165
	v_mul_f32_e32 v82, v84, v82
	v_cvt_pk_bf16_f32 v84, v82, v115
	v_add_co_u32_e32 v82, vcc, s82, v96
	v_fmac_f32_e32 v90, v94, v208
	s_nop 0
	v_addc_co_u32_e32 v83, vcc, 0, v97, vcc
	global_store_short v[82:83], v84, off offset:-4096
	s_waitcnt vmcnt(33)
	v_lshlrev_b32_e32 v84, 16, v161
	v_fmac_f32_e32 v210, v206, v209
	v_mul_f32_e32 v84, v90, v84
	v_fmac_f32_e32 v214, v210, v211
	v_cvt_pk_bf16_f32 v84, v84, v115
	global_store_short v[82:83], v84, off
	v_fmac_f32_e32 v88, v113, v214
	s_waitcnt vmcnt(32)
	v_lshlrev_b32_e32 v82, 16, v159
	v_mul_f32_e32 v82, v88, v82
	v_cvt_pk_bf16_f32 v84, v82, v115
	v_add_co_u32_e32 v82, vcc, s83, v96
	v_fmac_f32_e32 v86, v87, v214
	s_nop 0
	v_addc_co_u32_e32 v83, vcc, 0, v97, vcc
	global_store_short v[82:83], v84, off offset:-4096
	v_lshlrev_b32_e32 v84, 16, v154
	v_mul_f32_e32 v84, v86, v84
	v_cvt_pk_bf16_f32 v84, v84, v115
	global_store_short v[82:83], v84, off
	v_fmac_f32_e32 v92, v89, v214
	s_waitcnt vmcnt(33)
	v_lshlrev_b32_e32 v82, 16, v152
	v_mul_f32_e32 v82, v92, v82
	v_cvt_pk_bf16_f32 v84, v82, v115
	v_add_co_u32_e32 v82, vcc, s84, v96
	v_fmac_f32_e32 v93, v95, v214
	s_nop 0
	v_addc_co_u32_e32 v83, vcc, 0, v97, vcc
	global_store_short v[82:83], v84, off
	s_waitcnt vmcnt(33)
	v_lshlrev_b32_e32 v82, 16, v150
	v_mul_f32_e32 v82, v93, v82
	v_cvt_pk_bf16_f32 v84, v82, v115
	v_add_co_u32_e32 v82, vcc, 0x4c433000, v96
	s_waitcnt lgkmcnt(0)
	v_mov_b32_e32 v146, v216
	v_addc_co_u32_e32 v83, vcc, 0, v97, vcc
	s_add_u32 s0, s0, 0x40000
	v_fmac_f32_e32 v146, v210, v215
	s_addc_u32 s1, s1, 0
	s_and_b64 vcc, exec, s[44:45]
	global_store_short v[82:83], v84, off
	s_cbranch_vccnz .LBB0_442
	s_waitcnt vmcnt(31)
	v_mov_b32_e32 v176, v179
	s_waitcnt vmcnt(30)
	v_mov_b32_e32 v173, v180
	s_waitcnt vmcnt(29)
	v_mov_b32_e32 v177, v181
	s_waitcnt vmcnt(28)
	v_mov_b32_e32 v174, v182
	s_waitcnt vmcnt(27)
	v_mov_b32_e32 v178, v183
	s_waitcnt vmcnt(26)
	v_mov_b32_e32 v167, v184
	s_waitcnt vmcnt(25)
	v_mov_b32_e32 v175, v185
	s_waitcnt vmcnt(24)
	v_mov_b32_e32 v172, v186
	s_waitcnt vmcnt(23)
	v_mov_b32_e32 v168, v187
	s_waitcnt vmcnt(22)
	v_mov_b32_e32 v166, v188
	s_waitcnt vmcnt(21)
	v_mov_b32_e32 v165, v189
	s_waitcnt vmcnt(20)
	v_mov_b32_e32 v161, v190
	s_waitcnt vmcnt(19)
	v_mov_b32_e32 v159, v191
	s_waitcnt vmcnt(18)
	v_mov_b32_e32 v154, v192
	s_waitcnt vmcnt(17)
	v_mov_b32_e32 v152, v193
	s_waitcnt vmcnt(16)
	v_mov_b32_e32 v150, v194
	s_branch .LBB0_438
